# PE GEMM loop (P7, K=256): first iteration peeled with C=0 as well, accumulator zeroing removed
# speedup vs baseline: 1.0026x; 1.0026x over previous
; #define PG8_STAGE(bufoff, gbase, voff) do { _Pragma("unroll") for (int _i = 0; _i < 2; ++_i) \
;         __builtin_amdgcn_global_load_lds((const unsigned*)((const char*)(gbase) + (voff)[_i]), (LAS unsigned*)(lds + (bufoff) + ldsw + _i * 8192), 16, 0, 0); } while (0)
; #define PG8_LDA(dst, b, h) do { _Pragma("unroll") for (int m = 0; m < 4; ++m) _Pragma("unroll") for (int k = 0; k < 2; ++k) dst[m][k] = *(const LAS bf16x8*)(lds + PG8_SA(b, h) + aoff + m * 2048 + k * 1024); } while (0)
; #define PG8_LDB(dst, b, h) do { _Pragma("unroll") for (int n = 0; n < 2; ++n) _Pragma("unroll") for (int k = 0; k < 2; ++k) dst[n][k] = *(const LAS bf16x8*)(lds + PG8_SB(b, h) + boff + n * 2048 + k * 1024); } while (0)
; #define PG8_MMA(ai, bj, At, Bt) do { __builtin_amdgcn_s_setprio(1); _Pragma("unroll") for (int m = 0; m < 4; ++m) _Pragma("unroll") for (int n = 0; n < 2; ++n) _Pragma("unroll") for (int k = 0; k < 2; ++k) \
;         acc[ai][bj][m][n] = __builtin_amdgcn_mfma_f32_16x16x32_bf16(Bt[n][k], At[m][k], acc[ai][bj][m][n], 0, 0, 0); __builtin_amdgcn_s_setprio(0); } while (0)
; #define PG8_BAR __builtin_amdgcn_s_barrier()
; template <class Epi>
; __device__ __forceinline__ void gemm_phase(LAS unsigned char* lds, const Gemm g, const StaticOrder& S, const Epi& E) {
;     ...
;         const char* nA = has_next ? (const char*)g.A + (size_t)nxt.pm * tstepA + (size_t)nxt.kt0 * kstep : cA; const char* nB = has_next ? (const char*)g.Bt + (size_t)nxt.pn * tstepB + (size_t)nxt.kt0 * kstep : cB;
;         const int nt = cur.nkt;
;         for (int t = 0; t < nt; t += 2) {
;             const bool last = (t == nt - 2);
;             const char* a1 = cA + (size_t)(t + 1) * kstep;
;             const char* a2 = last ? nA : cA + (size_t)(t + 2) * kstep; const char* b2 = last ? nB : cB + (size_t)(t + 2) * kstep;
;             const char* a3 = a2 + kstep; const char* b3 = b2 + kstep;
;             PG8_LDB(B0, 0, 0); PG8_SCHED; PG8_LDA(At, 0, 0); PG8_STAGE(PG8_SA(1, 1), a1 + hstepA, voffA);
;             PG8_WAIT_L(8); PG8_BAR; PG8_WAIT_L(0); PG8_MMA(0, 0, At, B0); PG8_BAR; PG8_SCHED;
;             PG8_LDB(B1, 0, 1); PG8_STAGE(PG8_SB(0, 0), b2, voffB);
;             PG8_BAR; PG8_WAIT_L(0); PG8_MMA(0, 1, At, B1); PG8_BAR;
;             PG8_LDA(At, 0, 1); PG8_STAGE(PG8_SA(0, 0), a2, voffA);
;             PG8_BAR; PG8_WAIT_L(0); PG8_MMA(1, 0, At, B0); PG8_BAR; PG8_SCHED;
.LBB0_924:
	s_ashr_i32 s23, s22, 31
	v_cmp_lt_u64_e32 vcc, s[26:27], v[144:145]
	s_lshl_b64 s[26:27], s[22:23], 17
	s_add_u32 s23, s12, s26
	s_addc_u32 s25, s13, s27
	s_and_b64 s[26:27], vcc, exec
	s_cselect_b32 s27, s25, s37
	s_cselect_b32 s26, s23, s36
	s_ashr_i32 s25, s24, 31
	s_lshl_b64 s[28:29], s[24:25], 17
	s_add_u32 s23, s8, s28
	s_addc_u32 s25, s9, s29
	s_and_b64 s[28:29], vcc, exec
	s_cselect_b32 s29, s25, s39
	s_cselect_b32 s28, s23, s38
	s_mov_b32 s23, 0
	s_mov_b64 s[40:41], -1
	s_mov_b64 s[42:43], 0
	s_add_u32 s25, s36, s23
	s_addc_u32 s46, s37, 0
	s_add_u32 s47, s25, 0x100
	s_addc_u32 s54, s46, 0
	s_and_b64 s[44:45], s[42:43], exec
	s_cselect_b32 s55, s27, s54
	s_cselect_b32 s54, s26, s47
	s_add_u32 s23, s38, s23
	s_addc_u32 s44, s39, 0
	s_add_u32 s23, s23, 0x100
	s_addc_u32 s44, s44, 0
	s_and_b64 s[42:43], s[42:43], exec
	s_cselect_b32 s57, s29, s44
	s_cselect_b32 s56, s28, s23
	s_add_u32 s58, s25, 0x10080
	s_addc_u32 s59, s46, 0
	s_add_i32 s80, s67, s33
	s_add_i32 m0, s35, 0xc000
	s_add_i32 s79, s35, 0xe000
	s_add_i32 s78, s80, 0x2000
	s_add_u32 s46, s56, 0x10000
	s_addc_u32 s47, s57, 0
	s_add_i32 s75, s68, s33
	ds_read_b128 v[148:151], v153
	ds_read_b128 v[156:159], v153 offset:1024
	ds_read_b128 v[160:163], v153 offset:2048
	ds_read_b128 v[164:167], v153 offset:3072
	s_add_i32 s74, s75, 0x2000
	s_add_i32 s73, 0, 0x18000
	s_add_u32 s44, s54, 0x10000
	s_addc_u32 s45, s55, 0
	s_add_i32 s72, s73, s33
	s_add_i32 s25, 0, 0x1c000
	s_add_i32 s23, s72, 0x2000
	s_add_u32 s42, s56, 0x10080
	s_addc_u32 s43, s57, 0
	s_add_i32 s77, s25, s33
	s_add_i32 s76, s77, 0x2000
	v_lshl_add_u64 v[200:201], s[58:59], 0, v[142:143]
	ds_read_b128 v[168:171], v154
	ds_read_b128 v[172:175], v154 offset:1024
	ds_read_b128 v[176:179], v154 offset:2048
	ds_read_b128 v[180:183], v154 offset:3072
	ds_read_b128 v[184:187], v154 offset:4096
	ds_read_b128 v[188:191], v154 offset:5120
	ds_read_b128 v[192:195], v154 offset:6144
	ds_read_b128 v[196:199], v154 offset:7168
	global_load_lds_dwordx4 v[200:201], off
	v_lshl_add_u64 v[200:201], s[58:59], 0, v[138:139]
	s_mov_b32 m0, s79
	s_nop 0
	global_load_lds_dwordx4 v[200:201], off
	s_waitcnt lgkmcnt(8)
	s_barrier
	s_waitcnt lgkmcnt(0)
	s_setprio 1
	s_waitcnt lgkmcnt(0)
	v_mfma_f32_16x16x32_bf16 v[124:127], v[148:151], v[168:171], 0
	v_mfma_f32_16x16x32_bf16 v[120:123], v[160:163], v[168:171], 0
	v_mfma_f32_16x16x32_bf16 v[116:119], v[148:151], v[176:179], 0
	v_mfma_f32_16x16x32_bf16 v[108:111], v[160:163], v[176:179], 0
	v_mfma_f32_16x16x32_bf16 v[100:103], v[148:151], v[184:187], 0
	v_mfma_f32_16x16x32_bf16 v[92:95], v[160:163], v[184:187], 0
	v_mfma_f32_16x16x32_bf16 v[84:87], v[148:151], v[192:195], 0
	v_mfma_f32_16x16x32_bf16 v[76:79], v[160:163], v[192:195], 0
	v_mfma_f32_16x16x32_bf16 v[124:127], v[156:159], v[172:175], v[124:127]
	v_mfma_f32_16x16x32_bf16 v[120:123], v[164:167], v[172:175], v[120:123]
	v_mfma_f32_16x16x32_bf16 v[116:119], v[156:159], v[180:183], v[116:119]
	v_mfma_f32_16x16x32_bf16 v[108:111], v[164:167], v[180:183], v[108:111]
	v_mfma_f32_16x16x32_bf16 v[100:103], v[156:159], v[188:191], v[100:103]
	v_mfma_f32_16x16x32_bf16 v[92:95], v[164:167], v[188:191], v[92:95]
	v_mfma_f32_16x16x32_bf16 v[84:87], v[156:159], v[196:199], v[84:87]
	v_mfma_f32_16x16x32_bf16 v[76:79], v[164:167], v[196:199], v[76:79]
	s_setprio 0
	s_barrier
	s_mov_b32 m0, s80
	v_lshl_add_u64 v[216:217], s[56:57], 0, v[140:141]
	ds_read_b128 v[200:203], v155
	ds_read_b128 v[204:207], v155 offset:1024
	ds_read_b128 v[208:211], v155 offset:2048
	ds_read_b128 v[212:215], v155 offset:3072
	global_load_lds_dwordx4 v[216:217], off
	v_lshl_add_u64 v[218:219], s[56:57], 0, v[136:137]
	s_mov_b32 m0, s78
	s_nop 0
	global_load_lds_dwordx4 v[218:219], off
	s_barrier
	s_waitcnt lgkmcnt(0)
	s_setprio 1
	s_waitcnt lgkmcnt(0)
	v_mfma_f32_16x16x32_bf16 v[112:115], v[200:203], v[168:171], 0
	v_mfma_f32_16x16x32_bf16 v[104:107], v[208:211], v[168:171], 0
	v_mfma_f32_16x16x32_bf16 v[96:99], v[200:203], v[176:179], 0
	v_mfma_f32_16x16x32_bf16 v[88:91], v[208:211], v[176:179], 0
	v_mfma_f32_16x16x32_bf16 v[80:83], v[200:203], v[184:187], 0
	v_mfma_f32_16x16x32_bf16 v[72:75], v[208:211], v[184:187], 0
	v_mfma_f32_16x16x32_bf16 v[68:71], v[200:203], v[192:195], 0
	v_mfma_f32_16x16x32_bf16 v[64:67], v[208:211], v[192:195], 0
	v_mfma_f32_16x16x32_bf16 v[112:115], v[204:207], v[172:175], v[112:115]
	v_mfma_f32_16x16x32_bf16 v[104:107], v[212:215], v[172:175], v[104:107]
	v_mfma_f32_16x16x32_bf16 v[96:99], v[204:207], v[180:183], v[96:99]
	v_mfma_f32_16x16x32_bf16 v[88:91], v[212:215], v[180:183], v[88:91]
	v_mfma_f32_16x16x32_bf16 v[80:83], v[204:207], v[188:191], v[80:83]
	v_mfma_f32_16x16x32_bf16 v[72:75], v[212:215], v[188:191], v[72:75]
	v_mfma_f32_16x16x32_bf16 v[68:71], v[204:207], v[196:199], v[68:71]
	v_mfma_f32_16x16x32_bf16 v[64:67], v[212:215], v[196:199], v[64:67]
	s_setprio 0
	s_mov_b32 m0, s35
	v_lshl_add_u64 v[220:221], s[54:55], 0, v[142:143]
	s_barrier
	ds_read_b128 v[168:171], v154 offset:16384
	ds_read_b128 v[172:175], v154 offset:17408
	ds_read_b128 v[176:179], v154 offset:18432
	ds_read_b128 v[180:183], v154 offset:19456
	ds_read_b128 v[184:187], v154 offset:20480
	ds_read_b128 v[188:191], v154 offset:21504
	ds_read_b128 v[192:195], v154 offset:22528
	ds_read_b128 v[196:199], v154 offset:23552
	global_load_lds_dwordx4 v[220:221], off
	v_lshl_add_u64 v[222:223], s[54:55], 0, v[138:139]
	s_mov_b32 m0, s60
	s_nop 0
	global_load_lds_dwordx4 v[222:223], off
	s_barrier
; #define PG8_STAGE(bufoff, gbase, voff) do { _Pragma("unroll") for (int _i = 0; _i < 2; ++_i) \
;         __builtin_amdgcn_global_load_lds((const unsigned*)((const char*)(gbase) + (voff)[_i]), (LAS unsigned*)(lds + (bufoff) + ldsw + _i * 8192), 16, 0, 0); } while (0)
; #define PG8_LDA(dst, b, h) do { _Pragma("unroll") for (int m = 0; m < 4; ++m) _Pragma("unroll") for (int k = 0; k < 2; ++k) dst[m][k] = *(const LAS bf16x8*)(lds + PG8_SA(b, h) + aoff + m * 2048 + k * 1024); } while (0)
; #define PG8_LDB(dst, b, h) do { _Pragma("unroll") for (int n = 0; n < 2; ++n) _Pragma("unroll") for (int k = 0; k < 2; ++k) dst[n][k] = *(const LAS bf16x8*)(lds + PG8_SB(b, h) + boff + n * 2048 + k * 1024); } while (0)
; #define PG8_MMA(ai, bj, At, Bt) do { __builtin_amdgcn_s_setprio(1); _Pragma("unroll") for (int m = 0; m < 4; ++m) _Pragma("unroll") for (int n = 0; n < 2; ++n) _Pragma("unroll") for (int k = 0; k < 2; ++k) \
;         acc[ai][bj][m][n] = __builtin_amdgcn_mfma_f32_16x16x32_bf16(Bt[n][k], At[m][k], acc[ai][bj][m][n], 0, 0, 0); __builtin_amdgcn_s_setprio(0); } while (0)
; #define PG8_WAIT_V(n) asm volatile("s_waitcnt vmcnt(" #n ")" ::: "memory")
; #define PG8_WAIT_L(n) asm volatile("s_waitcnt lgkmcnt(" #n ")" ::: "memory")
; #define PG8_BAR __builtin_amdgcn_s_barrier()
; #define PG8_SCHED __builtin_amdgcn_sched_barrier(0)
; template <class Epi>
; __device__ __forceinline__ void gemm_phase(LAS unsigned char* lds, const Gemm g, const StaticOrder& S, const Epi& E) {
;     ...
;             PG8_BAR; PG8_WAIT_L(0); PG8_MMA(1, 0, At, B0); PG8_BAR; PG8_SCHED;
;             PG8_STAGE(PG8_SB(0, 1), b2 + hstepB, voffB);
;             PG8_WAIT_V(6); PG8_BAR; PG8_MMA(1, 1, At, B1); PG8_BAR;
;             PG8_LDB(B0, 1, 0); PG8_SCHED; PG8_LDA(At, 1, 0); PG8_STAGE(PG8_SA(0, 1), a2 + hstepA, voffA);
;             PG8_WAIT_L(8); PG8_BAR; PG8_WAIT_L(0); PG8_MMA(0, 0, At, B0); PG8_BAR; PG8_SCHED;
	s_waitcnt lgkmcnt(0)
	s_setprio 1
	s_waitcnt lgkmcnt(0)
	v_mfma_f32_16x16x32_bf16 v[60:63], v[148:151], v[168:171], 0
	v_mfma_f32_16x16x32_bf16 v[56:59], v[160:163], v[168:171], 0
	v_mfma_f32_16x16x32_bf16 v[52:55], v[148:151], v[176:179], 0
	v_mfma_f32_16x16x32_bf16 v[44:47], v[160:163], v[176:179], 0
	v_mfma_f32_16x16x32_bf16 v[36:39], v[148:151], v[184:187], 0
	v_mfma_f32_16x16x32_bf16 v[28:31], v[160:163], v[184:187], 0
	v_mfma_f32_16x16x32_bf16 v[20:23], v[148:151], v[192:195], 0
	v_mfma_f32_16x16x32_bf16 v[12:15], v[160:163], v[192:195], 0
	v_mfma_f32_16x16x32_bf16 v[60:63], v[156:159], v[172:175], v[60:63]
	v_mfma_f32_16x16x32_bf16 v[56:59], v[164:167], v[172:175], v[56:59]
	v_mfma_f32_16x16x32_bf16 v[52:55], v[156:159], v[180:183], v[52:55]
	v_mfma_f32_16x16x32_bf16 v[44:47], v[164:167], v[180:183], v[44:47]
	v_mfma_f32_16x16x32_bf16 v[36:39], v[156:159], v[188:191], v[36:39]
	v_mfma_f32_16x16x32_bf16 v[28:31], v[164:167], v[188:191], v[28:31]
	v_mfma_f32_16x16x32_bf16 v[20:23], v[156:159], v[196:199], v[20:23]
	v_mfma_f32_16x16x32_bf16 v[12:15], v[164:167], v[196:199], v[12:15]
	s_setprio 0
	s_barrier
	s_mov_b32 m0, s75
	v_lshl_add_u64 v[148:149], s[46:47], 0, v[140:141]
	global_load_lds_dwordx4 v[148:149], off
	v_lshl_add_u64 v[148:149], s[46:47], 0, v[136:137]
	s_mov_b32 m0, s74
	s_nop 0
	global_load_lds_dwordx4 v[148:149], off
	s_waitcnt vmcnt(6)
	s_barrier
	s_setprio 1
	v_mfma_f32_16x16x32_bf16 v[48:51], v[200:203], v[168:171], 0
	v_mfma_f32_16x16x32_bf16 v[40:43], v[208:211], v[168:171], 0
	v_mfma_f32_16x16x32_bf16 v[32:35], v[200:203], v[176:179], 0
	v_mfma_f32_16x16x32_bf16 v[24:27], v[208:211], v[176:179], 0
	v_mfma_f32_16x16x32_bf16 v[16:19], v[200:203], v[184:187], 0
	v_mfma_f32_16x16x32_bf16 v[8:11], v[208:211], v[184:187], 0
	v_mfma_f32_16x16x32_bf16 v[4:7], v[200:203], v[192:195], 0
	v_mfma_f32_16x16x32_bf16 v[0:3], v[208:211], v[192:195], 0
	v_mfma_f32_16x16x32_bf16 v[48:51], v[204:207], v[172:175], v[48:51]
	v_mfma_f32_16x16x32_bf16 v[40:43], v[212:215], v[172:175], v[40:43]
	v_mfma_f32_16x16x32_bf16 v[32:35], v[204:207], v[180:183], v[32:35]
	v_mfma_f32_16x16x32_bf16 v[24:27], v[212:215], v[180:183], v[24:27]
	v_mfma_f32_16x16x32_bf16 v[16:19], v[204:207], v[188:191], v[16:19]
	v_mfma_f32_16x16x32_bf16 v[8:11], v[212:215], v[188:191], v[8:11]
	v_mfma_f32_16x16x32_bf16 v[4:7], v[204:207], v[196:199], v[4:7]
	v_mfma_f32_16x16x32_bf16 v[0:3], v[212:215], v[196:199], v[0:3]
	s_setprio 0
	v_add_u32_e32 v164, s73, v135
	s_barrier
	ds_read_b128 v[148:151], v164
	ds_read_b128 v[156:159], v164 offset:1024
	ds_read_b128 v[160:163], v164 offset:2048
	ds_read_b128 v[164:167], v164 offset:3072
	s_mov_b32 m0, s61
	v_lshl_add_u64 v[200:201], s[44:45], 0, v[142:143]
	ds_read_b128 v[168:171], v154 offset:32768
	ds_read_b128 v[172:175], v154 offset:33792
	ds_read_b128 v[176:179], v154 offset:34816
	ds_read_b128 v[180:183], v154 offset:35840
	ds_read_b128 v[184:187], v154 offset:36864
	ds_read_b128 v[188:191], v154 offset:37888
	ds_read_b128 v[192:195], v154 offset:38912
	ds_read_b128 v[196:199], v154 offset:39936
	global_load_lds_dwordx4 v[200:201], off
	v_lshl_add_u64 v[200:201], s[44:45], 0, v[138:139]
	s_mov_b32 m0, s62
	s_nop 0
	global_load_lds_dwordx4 v[200:201], off
	s_waitcnt lgkmcnt(8)
	s_barrier
	s_waitcnt lgkmcnt(0)
	s_setprio 1
	s_waitcnt lgkmcnt(0)
	v_mfma_f32_16x16x32_bf16 v[124:127], v[148:151], v[168:171], v[124:127]
	v_mfma_f32_16x16x32_bf16 v[120:123], v[160:163], v[168:171], v[120:123]
	v_mfma_f32_16x16x32_bf16 v[116:119], v[148:151], v[176:179], v[116:119]
	v_mfma_f32_16x16x32_bf16 v[108:111], v[160:163], v[176:179], v[108:111]
	v_mfma_f32_16x16x32_bf16 v[100:103], v[148:151], v[184:187], v[100:103]
	v_mfma_f32_16x16x32_bf16 v[92:95], v[160:163], v[184:187], v[92:95]
	v_mfma_f32_16x16x32_bf16 v[84:87], v[148:151], v[192:195], v[84:87]
	v_mfma_f32_16x16x32_bf16 v[76:79], v[160:163], v[192:195], v[76:79]
	v_mfma_f32_16x16x32_bf16 v[124:127], v[156:159], v[172:175], v[124:127]
	v_mfma_f32_16x16x32_bf16 v[120:123], v[164:167], v[172:175], v[120:123]
	v_mfma_f32_16x16x32_bf16 v[116:119], v[156:159], v[180:183], v[116:119]
	v_mfma_f32_16x16x32_bf16 v[108:111], v[164:167], v[180:183], v[108:111]
	v_mfma_f32_16x16x32_bf16 v[100:103], v[156:159], v[188:191], v[100:103]
	v_mfma_f32_16x16x32_bf16 v[92:95], v[164:167], v[188:191], v[92:95]
	v_mfma_f32_16x16x32_bf16 v[84:87], v[156:159], v[196:199], v[84:87]
	v_mfma_f32_16x16x32_bf16 v[76:79], v[164:167], v[196:199], v[76:79]
	s_setprio 0
	s_barrier
; #define PG8_STAGE(bufoff, gbase, voff) do { _Pragma("unroll") for (int _i = 0; _i < 2; ++_i) \
;         __builtin_amdgcn_global_load_lds((const unsigned*)((const char*)(gbase) + (voff)[_i]), (LAS unsigned*)(lds + (bufoff) + ldsw + _i * 8192), 16, 0, 0); } while (0)
; #define PG8_LDA(dst, b, h) do { _Pragma("unroll") for (int m = 0; m < 4; ++m) _Pragma("unroll") for (int k = 0; k < 2; ++k) dst[m][k] = *(const LAS bf16x8*)(lds + PG8_SA(b, h) + aoff + m * 2048 + k * 1024); } while (0)
; #define PG8_LDB(dst, b, h) do { _Pragma("unroll") for (int n = 0; n < 2; ++n) _Pragma("unroll") for (int k = 0; k < 2; ++k) dst[n][k] = *(const LAS bf16x8*)(lds + PG8_SB(b, h) + boff + n * 2048 + k * 1024); } while (0)
; #define PG8_MMA(ai, bj, At, Bt) do { __builtin_amdgcn_s_setprio(1); _Pragma("unroll") for (int m = 0; m < 4; ++m) _Pragma("unroll") for (int n = 0; n < 2; ++n) _Pragma("unroll") for (int k = 0; k < 2; ++k) \
;         acc[ai][bj][m][n] = __builtin_amdgcn_mfma_f32_16x16x32_bf16(Bt[n][k], At[m][k], acc[ai][bj][m][n], 0, 0, 0); __builtin_amdgcn_s_setprio(0); } while (0)
; #define PG8_WAIT_V(n) asm volatile("s_waitcnt vmcnt(" #n ")" ::: "memory")
; #define PG8_WAIT_L(n) asm volatile("s_waitcnt lgkmcnt(" #n ")" ::: "memory")
; #define PG8_BAR __builtin_amdgcn_s_barrier()
; #define PG8_SCHED __builtin_amdgcn_sched_barrier(0)
; template <class Epi>
; __device__ __forceinline__ void gemm_phase(LAS unsigned char* lds, const Gemm g, const StaticOrder& S, const Epi& E) {
;     ...
;             PG8_WAIT_L(8); PG8_BAR; PG8_WAIT_L(0); PG8_MMA(0, 0, At, B0); PG8_BAR; PG8_SCHED;
;             PG8_LDB(B1, 1, 1); PG8_STAGE(PG8_SB(1, 0), b3, voffB);
;             PG8_BAR; PG8_WAIT_L(0); PG8_MMA(0, 1, At, B1); PG8_BAR;
;             PG8_LDA(At, 1, 1); PG8_STAGE(PG8_SA(1, 0), a3, voffA);
;             PG8_BAR; PG8_WAIT_L(0); PG8_MMA(1, 0, At, B0); PG8_BAR; PG8_SCHED;
;             PG8_STAGE(PG8_SB(1, 1), b3 + hstepB, voffB);
;             PG8_WAIT_V(6); PG8_BAR; PG8_MMA(1, 1, At, B1); PG8_BAR;
;         }
	s_mov_b32 m0, s72
	v_add_u32_e32 v212, s25, v135
	v_lshl_add_u64 v[216:217], v[216:217], 0, s[18:19]
	ds_read_b128 v[200:203], v212
	ds_read_b128 v[204:207], v212 offset:1024
	ds_read_b128 v[208:211], v212 offset:2048
	ds_read_b128 v[212:215], v212 offset:3072
	global_load_lds_dwordx4 v[216:217], off
	v_lshl_add_u64 v[216:217], v[218:219], 0, s[18:19]
	s_mov_b32 m0, s23
	s_nop 0
	global_load_lds_dwordx4 v[216:217], off
	s_barrier
	s_waitcnt lgkmcnt(0)
	s_setprio 1
	s_waitcnt lgkmcnt(0)
	v_mfma_f32_16x16x32_bf16 v[112:115], v[200:203], v[168:171], v[112:115]
	v_mfma_f32_16x16x32_bf16 v[104:107], v[208:211], v[168:171], v[104:107]
	v_mfma_f32_16x16x32_bf16 v[96:99], v[200:203], v[176:179], v[96:99]
	v_mfma_f32_16x16x32_bf16 v[88:91], v[208:211], v[176:179], v[88:91]
	v_mfma_f32_16x16x32_bf16 v[80:83], v[200:203], v[184:187], v[80:83]
	v_mfma_f32_16x16x32_bf16 v[72:75], v[208:211], v[184:187], v[72:75]
	v_mfma_f32_16x16x32_bf16 v[68:71], v[200:203], v[192:195], v[68:71]
	v_mfma_f32_16x16x32_bf16 v[64:67], v[208:211], v[192:195], v[64:67]
	v_mfma_f32_16x16x32_bf16 v[112:115], v[204:207], v[172:175], v[112:115]
	v_mfma_f32_16x16x32_bf16 v[104:107], v[212:215], v[172:175], v[104:107]
	v_mfma_f32_16x16x32_bf16 v[96:99], v[204:207], v[180:183], v[96:99]
	v_mfma_f32_16x16x32_bf16 v[88:91], v[212:215], v[180:183], v[88:91]
	v_mfma_f32_16x16x32_bf16 v[80:83], v[204:207], v[188:191], v[80:83]
	v_mfma_f32_16x16x32_bf16 v[72:75], v[212:215], v[188:191], v[72:75]
	v_mfma_f32_16x16x32_bf16 v[68:71], v[204:207], v[196:199], v[68:71]
	v_mfma_f32_16x16x32_bf16 v[64:67], v[212:215], v[196:199], v[64:67]
	s_setprio 0
	s_mov_b32 m0, s65
	v_lshl_add_u64 v[216:217], v[220:221], 0, s[18:19]
	s_barrier
	ds_read_b128 v[168:171], v154 offset:49152
	ds_read_b128 v[172:175], v154 offset:50176
	ds_read_b128 v[176:179], v154 offset:51200
	ds_read_b128 v[180:183], v154 offset:52224
	ds_read_b128 v[184:187], v154 offset:53248
	ds_read_b128 v[188:191], v154 offset:54272
	ds_read_b128 v[192:195], v154 offset:55296
	ds_read_b128 v[196:199], v154 offset:56320
	global_load_lds_dwordx4 v[216:217], off
	v_lshl_add_u64 v[216:217], v[222:223], 0, s[18:19]
	s_mov_b32 m0, s66
	s_nop 0
	global_load_lds_dwordx4 v[216:217], off
	s_barrier
	s_waitcnt lgkmcnt(0)
	s_setprio 1
	s_waitcnt lgkmcnt(0)
	v_mfma_f32_16x16x32_bf16 v[60:63], v[148:151], v[168:171], v[60:63]
	v_mfma_f32_16x16x32_bf16 v[56:59], v[160:163], v[168:171], v[56:59]
	v_mfma_f32_16x16x32_bf16 v[52:55], v[148:151], v[176:179], v[52:55]
	v_mfma_f32_16x16x32_bf16 v[44:47], v[160:163], v[176:179], v[44:47]
	v_mfma_f32_16x16x32_bf16 v[36:39], v[148:151], v[184:187], v[36:39]
	v_mfma_f32_16x16x32_bf16 v[28:31], v[160:163], v[184:187], v[28:31]
	v_mfma_f32_16x16x32_bf16 v[20:23], v[148:151], v[192:195], v[20:23]
	v_mfma_f32_16x16x32_bf16 v[12:15], v[160:163], v[192:195], v[12:15]
	v_mfma_f32_16x16x32_bf16 v[60:63], v[156:159], v[172:175], v[60:63]
	v_mfma_f32_16x16x32_bf16 v[56:59], v[164:167], v[172:175], v[56:59]
	v_mfma_f32_16x16x32_bf16 v[52:55], v[156:159], v[180:183], v[52:55]
	v_mfma_f32_16x16x32_bf16 v[44:47], v[164:167], v[180:183], v[44:47]
	v_mfma_f32_16x16x32_bf16 v[36:39], v[156:159], v[188:191], v[36:39]
	v_mfma_f32_16x16x32_bf16 v[28:31], v[164:167], v[188:191], v[28:31]
	v_mfma_f32_16x16x32_bf16 v[20:23], v[156:159], v[196:199], v[20:23]
	v_mfma_f32_16x16x32_bf16 v[12:15], v[164:167], v[196:199], v[12:15]
	s_setprio 0
	s_barrier
	s_mov_b32 m0, s77
	v_lshl_add_u64 v[148:149], s[42:43], 0, v[140:141]
	global_load_lds_dwordx4 v[148:149], off
	v_lshl_add_u64 v[148:149], s[42:43], 0, v[136:137]
	s_mov_b32 m0, s76
	s_nop 0
	global_load_lds_dwordx4 v[148:149], off
	s_waitcnt vmcnt(6)
	s_barrier
	s_setprio 1
	v_mfma_f32_16x16x32_bf16 v[48:51], v[200:203], v[168:171], v[48:51]
	v_mfma_f32_16x16x32_bf16 v[40:43], v[208:211], v[168:171], v[40:43]
	v_mfma_f32_16x16x32_bf16 v[32:35], v[200:203], v[176:179], v[32:35]
	v_mfma_f32_16x16x32_bf16 v[24:27], v[208:211], v[176:179], v[24:27]
	v_mfma_f32_16x16x32_bf16 v[16:19], v[200:203], v[184:187], v[16:19]
	v_mfma_f32_16x16x32_bf16 v[8:11], v[208:211], v[184:187], v[8:11]
	v_mfma_f32_16x16x32_bf16 v[4:7], v[200:203], v[192:195], v[4:7]
	v_mfma_f32_16x16x32_bf16 v[0:3], v[208:211], v[192:195], v[0:3]
	v_mfma_f32_16x16x32_bf16 v[48:51], v[204:207], v[172:175], v[48:51]
	v_mfma_f32_16x16x32_bf16 v[40:43], v[212:215], v[172:175], v[40:43]
	v_mfma_f32_16x16x32_bf16 v[32:35], v[204:207], v[180:183], v[32:35]
	v_mfma_f32_16x16x32_bf16 v[24:27], v[212:215], v[180:183], v[24:27]
	v_mfma_f32_16x16x32_bf16 v[16:19], v[204:207], v[188:191], v[16:19]
	v_mfma_f32_16x16x32_bf16 v[8:11], v[212:215], v[188:191], v[8:11]
	v_mfma_f32_16x16x32_bf16 v[4:7], v[204:207], v[196:199], v[4:7]
	v_mfma_f32_16x16x32_bf16 v[0:3], v[212:215], v[196:199], v[0:3]
	s_setprio 0
	s_movk_i32 s23, 0x100
	s_andn2_b64 vcc, exec, s[40:41]
	s_mov_b64 s[42:43], -1
	s_mov_b64 s[40:41], 0
	s_barrier
